# in-projection GEMM epilogue (head RMS norm): the two cross-row lane shuffles per block done with v_permlane16_swap / v_permlane32_swap instead of ds_bpermute (32 LDS round trips less per tile)
# speedup vs baseline: 1.0037x; 1.0035x over previous
; #define LAS __attribute__((address_space(3)))
;     __device__ __forceinline__ void operator()(const f32x4 (&acc)[2][2][4][2], const Unit& u, int wr, int wc, int fr, int fq) const {
;     ...
; #pragma unroll
;         for (int ai = 0; ai < 2; ++ai)
; #pragma unroll
;             for (int m = 0; m < 4; ++m)
; #pragma unroll
;                 for (int bj = 0; bj < 2; ++bj) {
;                     const f32x4 v0 = acc[ai][bj][m][0], v1 = acc[ai][bj][m][1];
;                     float t = v0[0] * v0[0] + v0[1] * v0[1] + v0[2] * v0[2] + v0[3] * v0[3] + v1[0] * v1[0] + v1[1] * v1[1] + v1[2] * v1[2] + v1[3] * v1[3];
;                     t += __shfl_xor(t, 16); t += __shfl_xor(t, 32);
;                     if (fq == 0) *(LAS float*)(Pb + pown + ((ai * 4 + m) * 2 + bj) * 64) = t;
;                 }
.LBB0_853:
	v_mul_f32_e32 v145, v127, v127
	v_fmac_f32_e32 v145, v126, v126
	v_fmac_f32_e32 v145, v128, v128
	v_fmac_f32_e32 v145, v129, v129
	v_fmac_f32_e32 v145, v122, v122
	v_cmp_lt_i32_e32 vcc, v204, v199
	v_fmac_f32_e32 v145, v123, v123
	v_fmac_f32_e32 v145, v124, v124
	v_cndmask_b32_e32 v0, v197, v204, vcc
	v_lshlrev_b32_e32 v0, 2, v0
	v_fmac_f32_e32 v145, v125, v125
	v_mov_b32_e32 v146, v145
	s_nop 1
	v_permlane16_swap_b32_e32 v145, v146
	v_add_f32_e32 v145, v145, v146
	v_cmp_lt_i32_e32 vcc, v205, v199
	v_mov_b32_e32 v160, v155
	v_mov_b32_e32 v159, v156
	v_cndmask_b32_e32 v144, v197, v205, vcc
	v_lshlrev_b32_e32 v144, 2, v144
	v_mov_b32_e32 v146, v145
	s_nop 1
	v_permlane32_swap_b32_e32 v145, v146
	s_and_saveexec_b64 s[40:41], s[36:37]
	s_cbranch_execz .LBB0_855
	v_add_f32_e32 v145, v145, v146
	v_add_u32_e32 v146, 0, v160
	v_add_u32_e32 v146, 0x21900, v146
	ds_write_b32 v146, v145
.LBB0_855:
	s_or_b64 exec, exec, s[40:41]
	v_mul_f32_e32 v145, v63, v63
	v_fmac_f32_e32 v145, v62, v62
	v_fmac_f32_e32 v145, v64, v64
	v_fmac_f32_e32 v145, v65, v65
	v_fmac_f32_e32 v145, v58, v58
	v_fmac_f32_e32 v145, v59, v59
	v_fmac_f32_e32 v145, v60, v60
	v_fmac_f32_e32 v145, v61, v61
	v_mov_b32_e32 v146, v145
	s_nop 1
	v_permlane16_swap_b32_e32 v145, v146
	v_add_f32_e32 v145, v145, v146
	v_mov_b32_e32 v146, v145
	s_nop 1
	v_permlane32_swap_b32_e32 v145, v146
	s_and_saveexec_b64 s[40:41], s[36:37]
	s_cbranch_execz .LBB0_857
	s_add_i32 s21, 0, 0x21900
	v_add_f32_e32 v145, v145, v146
	v_add_u32_e32 v146, s21, v160
	ds_write_b32 v146, v145 offset:64
.LBB0_857:
	s_or_b64 exec, exec, s[40:41]
	v_mul_f32_e32 v145, v119, v119
	v_fmac_f32_e32 v145, v118, v118
	v_fmac_f32_e32 v145, v120, v120
	v_fmac_f32_e32 v145, v121, v121
	v_fmac_f32_e32 v145, v114, v114
	v_fmac_f32_e32 v145, v115, v115
	v_fmac_f32_e32 v145, v116, v116
	v_fmac_f32_e32 v145, v117, v117
	v_mov_b32_e32 v146, v145
	s_nop 1
	v_permlane16_swap_b32_e32 v145, v146
	v_add_f32_e32 v145, v145, v146
	v_mov_b32_e32 v146, v145
	s_nop 1
	v_permlane32_swap_b32_e32 v145, v146
	s_and_saveexec_b64 s[40:41], s[36:37]
	s_cbranch_execz .LBB0_859
	s_add_i32 s21, 0, 0x21900
	v_add_f32_e32 v145, v145, v146
	v_add_u32_e32 v146, s21, v160
	ds_write_b32 v146, v145 offset:128
.LBB0_859:
	s_or_b64 exec, exec, s[40:41]
	v_mul_f32_e32 v145, v55, v55
	v_fmac_f32_e32 v145, v54, v54
	v_fmac_f32_e32 v145, v56, v56
	v_fmac_f32_e32 v145, v57, v57
	v_fmac_f32_e32 v145, v50, v50
	v_fmac_f32_e32 v145, v51, v51
	v_fmac_f32_e32 v145, v52, v52
	v_fmac_f32_e32 v145, v53, v53
	v_mov_b32_e32 v146, v145
	s_nop 1
	v_permlane16_swap_b32_e32 v145, v146
	v_add_f32_e32 v145, v145, v146
	v_mov_b32_e32 v146, v145
	s_nop 1
	v_permlane32_swap_b32_e32 v145, v146
	s_and_saveexec_b64 s[40:41], s[36:37]
	s_cbranch_execz .LBB0_861
	s_add_i32 s21, 0, 0x21900
	v_add_f32_e32 v145, v145, v146
	v_add_u32_e32 v146, s21, v160
	ds_write_b32 v146, v145 offset:192
.LBB0_861:
	s_or_b64 exec, exec, s[40:41]
	v_mul_f32_e32 v145, v111, v111
	v_fmac_f32_e32 v145, v110, v110
	v_fmac_f32_e32 v145, v112, v112
	v_fmac_f32_e32 v145, v113, v113
	v_fmac_f32_e32 v145, v106, v106
	v_fmac_f32_e32 v145, v107, v107
	v_fmac_f32_e32 v145, v108, v108
	v_fmac_f32_e32 v145, v109, v109
	v_mov_b32_e32 v146, v145
	s_nop 1
	v_permlane16_swap_b32_e32 v145, v146
	v_add_f32_e32 v145, v145, v146
	v_mov_b32_e32 v146, v145
	s_nop 1
	v_permlane32_swap_b32_e32 v145, v146
	s_and_saveexec_b64 s[40:41], s[36:37]
	s_cbranch_execz .LBB0_863
	s_add_i32 s21, 0, 0x21900
	v_add_f32_e32 v145, v145, v146
	v_add_u32_e32 v146, s21, v160
	ds_write_b32 v146, v145 offset:256
.LBB0_863:
	s_or_b64 exec, exec, s[40:41]
	v_mul_f32_e32 v145, v47, v47
	v_fmac_f32_e32 v145, v46, v46
	v_fmac_f32_e32 v145, v48, v48
	v_fmac_f32_e32 v145, v49, v49
	v_fmac_f32_e32 v145, v42, v42
	v_fmac_f32_e32 v145, v43, v43
	v_fmac_f32_e32 v145, v44, v44
	v_fmac_f32_e32 v145, v45, v45
	v_mov_b32_e32 v146, v145
	s_nop 1
	v_permlane16_swap_b32_e32 v145, v146
	v_add_f32_e32 v145, v145, v146
	v_mov_b32_e32 v146, v145
	s_nop 1
	v_permlane32_swap_b32_e32 v145, v146
	s_and_saveexec_b64 s[40:41], s[36:37]
	s_cbranch_execz .LBB0_865
	s_add_i32 s21, 0, 0x21900
	v_add_f32_e32 v145, v145, v146
	v_add_u32_e32 v146, s21, v160
	ds_write_b32 v146, v145 offset:320
.LBB0_865:
	s_or_b64 exec, exec, s[40:41]
	v_mul_f32_e32 v145, v103, v103
	v_fmac_f32_e32 v145, v102, v102
	v_fmac_f32_e32 v145, v104, v104
	v_fmac_f32_e32 v145, v105, v105
	v_fmac_f32_e32 v145, v98, v98
	v_fmac_f32_e32 v145, v99, v99
	v_fmac_f32_e32 v145, v100, v100
	v_fmac_f32_e32 v145, v101, v101
	v_mov_b32_e32 v146, v145
	s_nop 1
	v_permlane16_swap_b32_e32 v145, v146
	v_add_f32_e32 v145, v145, v146
	v_mov_b32_e32 v146, v145
	s_nop 1
	v_permlane32_swap_b32_e32 v145, v146
	s_and_saveexec_b64 s[40:41], s[36:37]
	s_cbranch_execz .LBB0_867
	s_add_i32 s21, 0, 0x21900
	v_add_f32_e32 v145, v145, v146
	v_add_u32_e32 v146, s21, v160
	ds_write_b32 v146, v145 offset:384
.LBB0_867:
	s_or_b64 exec, exec, s[40:41]
	v_mul_f32_e32 v145, v39, v39
	v_fmac_f32_e32 v145, v38, v38
	v_fmac_f32_e32 v145, v40, v40
	v_fmac_f32_e32 v145, v41, v41
	v_fmac_f32_e32 v145, v34, v34
	v_fmac_f32_e32 v145, v35, v35
	v_fmac_f32_e32 v145, v36, v36
	v_fmac_f32_e32 v145, v37, v37
	v_mov_b32_e32 v146, v145
	s_nop 1
	v_permlane16_swap_b32_e32 v145, v146
	v_add_f32_e32 v145, v145, v146
	v_mov_b32_e32 v146, v145
	s_nop 1
	v_permlane32_swap_b32_e32 v145, v146
	s_and_saveexec_b64 s[40:41], s[36:37]
	s_cbranch_execz .LBB0_869
	s_add_i32 s21, 0, 0x21900
	v_add_f32_e32 v145, v145, v146
	v_add_u32_e32 v146, s21, v160
	ds_write_b32 v146, v145 offset:448
; #define LAS __attribute__((address_space(3)))
;     __device__ __forceinline__ void operator()(const f32x4 (&acc)[2][2][4][2], const Unit& u, int wr, int wc, int fr, int fq) const {
;     ...
; #pragma unroll
;         for (int ai = 0; ai < 2; ++ai)
; #pragma unroll
;             for (int m = 0; m < 4; ++m)
; #pragma unroll
;                 for (int bj = 0; bj < 2; ++bj) {
;                     const f32x4 v0 = acc[ai][bj][m][0], v1 = acc[ai][bj][m][1];
;                     float t = v0[0] * v0[0] + v0[1] * v0[1] + v0[2] * v0[2] + v0[3] * v0[3] + v1[0] * v1[0] + v1[1] * v1[1] + v1[2] * v1[2] + v1[3] * v1[3];
;                     t += __shfl_xor(t, 16); t += __shfl_xor(t, 32);
;                     if (fq == 0) *(LAS float*)(Pb + pown + ((ai * 4 + m) * 2 + bj) * 64) = t;
;                 }
.LBB0_869:
	s_or_b64 exec, exec, s[40:41]
	v_mul_f32_e32 v145, v95, v95
	v_fmac_f32_e32 v145, v94, v94
	v_fmac_f32_e32 v145, v96, v96
	v_fmac_f32_e32 v145, v97, v97
	v_fmac_f32_e32 v145, v90, v90
	v_fmac_f32_e32 v145, v91, v91
	v_fmac_f32_e32 v145, v92, v92
	v_fmac_f32_e32 v145, v93, v93
	v_mov_b32_e32 v146, v145
	s_nop 1
	v_permlane16_swap_b32_e32 v145, v146
	v_add_f32_e32 v145, v145, v146
	v_mov_b32_e32 v146, v145
	s_nop 1
	v_permlane32_swap_b32_e32 v145, v146
	s_and_saveexec_b64 s[40:41], s[36:37]
	s_cbranch_execz .LBB0_871
	s_add_i32 s21, 0, 0x21900
	v_add_f32_e32 v145, v145, v146
	v_add_u32_e32 v146, s21, v160
	ds_write_b32 v146, v145 offset:512
.LBB0_871:
	s_or_b64 exec, exec, s[40:41]
	v_mul_f32_e32 v145, v31, v31
	v_fmac_f32_e32 v145, v30, v30
	v_fmac_f32_e32 v145, v32, v32
	v_fmac_f32_e32 v145, v33, v33
	v_fmac_f32_e32 v145, v26, v26
	v_fmac_f32_e32 v145, v27, v27
	v_fmac_f32_e32 v145, v28, v28
	v_fmac_f32_e32 v145, v29, v29
	v_mov_b32_e32 v146, v145
	s_nop 1
	v_permlane16_swap_b32_e32 v145, v146
	v_add_f32_e32 v145, v145, v146
	v_mov_b32_e32 v146, v145
	s_nop 1
	v_permlane32_swap_b32_e32 v145, v146
	s_and_saveexec_b64 s[40:41], s[36:37]
	s_cbranch_execz .LBB0_873
	s_add_i32 s21, 0, 0x21900
	v_add_f32_e32 v145, v145, v146
	v_add_u32_e32 v146, s21, v160
	ds_write_b32 v146, v145 offset:576
.LBB0_873:
	s_or_b64 exec, exec, s[40:41]
	v_mul_f32_e32 v145, v87, v87
	v_fmac_f32_e32 v145, v86, v86
	v_fmac_f32_e32 v145, v88, v88
	v_fmac_f32_e32 v145, v89, v89
	v_fmac_f32_e32 v145, v82, v82
	v_fmac_f32_e32 v145, v83, v83
	v_fmac_f32_e32 v145, v84, v84
	v_fmac_f32_e32 v145, v85, v85
	v_mov_b32_e32 v146, v145
	s_nop 1
	v_permlane16_swap_b32_e32 v145, v146
	v_add_f32_e32 v145, v145, v146
	v_mov_b32_e32 v146, v145
	s_nop 1
	v_permlane32_swap_b32_e32 v145, v146
	s_and_saveexec_b64 s[40:41], s[36:37]
	s_cbranch_execz .LBB0_875
	s_add_i32 s21, 0, 0x21900
	v_add_f32_e32 v145, v145, v146
	v_add_u32_e32 v146, s21, v160
	ds_write_b32 v146, v145 offset:640
.LBB0_875:
	s_or_b64 exec, exec, s[40:41]
	v_mul_f32_e32 v145, v23, v23
	v_fmac_f32_e32 v145, v22, v22
	v_fmac_f32_e32 v145, v24, v24
	v_fmac_f32_e32 v145, v25, v25
	v_fmac_f32_e32 v145, v18, v18
	v_fmac_f32_e32 v145, v19, v19
	v_fmac_f32_e32 v145, v20, v20
	v_fmac_f32_e32 v145, v21, v21
	v_mov_b32_e32 v146, v145
	s_nop 1
	v_permlane16_swap_b32_e32 v145, v146
	v_add_f32_e32 v145, v145, v146
	v_mov_b32_e32 v146, v145
	s_nop 1
	v_permlane32_swap_b32_e32 v145, v146
	s_and_saveexec_b64 s[40:41], s[36:37]
	s_cbranch_execz .LBB0_877
	s_add_i32 s21, 0, 0x21900
	v_add_f32_e32 v145, v145, v146
	v_add_u32_e32 v146, s21, v160
	ds_write_b32 v146, v145 offset:704
.LBB0_877:
	s_or_b64 exec, exec, s[40:41]
	v_mul_f32_e32 v145, v79, v79
	v_fmac_f32_e32 v145, v78, v78
	v_fmac_f32_e32 v145, v80, v80
	v_fmac_f32_e32 v145, v81, v81
	v_fmac_f32_e32 v145, v74, v74
	v_fmac_f32_e32 v145, v75, v75
	v_fmac_f32_e32 v145, v76, v76
	v_fmac_f32_e32 v145, v77, v77
	v_mov_b32_e32 v146, v145
	s_nop 1
	v_permlane16_swap_b32_e32 v145, v146
	v_add_f32_e32 v145, v145, v146
	v_mov_b32_e32 v146, v145
	s_nop 1
	v_permlane32_swap_b32_e32 v145, v146
	s_and_saveexec_b64 s[40:41], s[36:37]
	s_cbranch_execz .LBB0_879
	s_add_i32 s21, 0, 0x21900
	v_add_f32_e32 v145, v145, v146
	v_add_u32_e32 v146, s21, v160
	ds_write_b32 v146, v145 offset:768
.LBB0_879:
	s_or_b64 exec, exec, s[40:41]
	v_mul_f32_e32 v145, v15, v15
	v_fmac_f32_e32 v145, v14, v14
	v_fmac_f32_e32 v145, v16, v16
	v_fmac_f32_e32 v145, v17, v17
	v_fmac_f32_e32 v145, v10, v10
	v_fmac_f32_e32 v145, v11, v11
	v_fmac_f32_e32 v145, v12, v12
	v_fmac_f32_e32 v145, v13, v13
	v_mov_b32_e32 v146, v145
	s_nop 1
	v_permlane16_swap_b32_e32 v145, v146
	v_add_f32_e32 v145, v145, v146
	v_mov_b32_e32 v146, v145
	s_nop 1
	v_permlane32_swap_b32_e32 v145, v146
	s_and_saveexec_b64 s[40:41], s[36:37]
	s_cbranch_execz .LBB0_881
	s_add_i32 s21, 0, 0x21900
	v_add_f32_e32 v145, v145, v146
	v_add_u32_e32 v146, s21, v160
	ds_write_b32 v146, v145 offset:832
.LBB0_881:
	s_or_b64 exec, exec, s[40:41]
	v_mul_f32_e32 v145, v71, v71
	v_fmac_f32_e32 v145, v70, v70
	v_fmac_f32_e32 v145, v72, v72
	v_fmac_f32_e32 v145, v73, v73
	v_fmac_f32_e32 v145, v66, v66
	v_fmac_f32_e32 v145, v67, v67
	v_fmac_f32_e32 v145, v68, v68
	v_fmac_f32_e32 v145, v69, v69
	v_mov_b32_e32 v146, v145
	s_nop 1
	v_permlane16_swap_b32_e32 v145, v146
	v_add_f32_e32 v145, v145, v146
	v_mov_b32_e32 v146, v145
	s_nop 1
	v_permlane32_swap_b32_e32 v145, v146
	s_and_saveexec_b64 s[40:41], s[36:37]
	s_cbranch_execz .LBB0_883
	s_add_i32 s21, 0, 0x21900
	v_add_f32_e32 v145, v145, v146
	v_add_u32_e32 v146, s21, v160
	ds_write_b32 v146, v145 offset:896
.LBB0_883:
	s_or_b64 exec, exec, s[40:41]
	v_mul_f32_e32 v145, v7, v7
	v_fmac_f32_e32 v145, v6, v6
	v_fmac_f32_e32 v145, v8, v8
	v_fmac_f32_e32 v145, v9, v9
	v_fmac_f32_e32 v145, v2, v2
	v_fmac_f32_e32 v145, v3, v3
	v_fmac_f32_e32 v145, v4, v4
	v_fmac_f32_e32 v145, v5, v5
	v_mov_b32_e32 v0, v145
	s_nop 1
	v_permlane16_swap_b32_e32 v145, v0
	v_add_f32_e32 v0, v145, v0
	v_mov_b32_e32 v144, v0
	s_nop 1
	v_permlane32_swap_b32_e32 v0, v144
	s_and_saveexec_b64 s[40:41], s[36:37]
	s_cbranch_execz .LBB0_885
	s_add_i32 s21, 0, 0x21900
	v_add_f32_e32 v0, v0, v144
	v_add_u32_e32 v144, s21, v160
	ds_write_b32 v144, v0 offset:960
